# row passes P6/P9/P12: gain-vector loads hoisted out of the row loop, next-row prefetch now overlaps the reduction (single vmcnt(0) before first store)
# speedup vs baseline: 1.0004x; 1.0004x over previous
; #define RP_LOAD4(dst, ptr) do { _Pragma("unroll") for (int j = 0; j < 4; ++j) dst[j] = *(const v4u*)((ptr) + j * 512 + lane * 8); } while (0)
; #define RP_LOADX(dst, ptr) do { _Pragma("unroll") for (int j = 0; j < 4; ++j) { dst[2 * j] = *(const f32x4*)((ptr) + j * 512 + lane * 8); dst[2 * j + 1] = *(const f32x4*)((ptr) + j * 512 + lane * 8 + 4); } } while (0)
; __global__ void __launch_bounds__(NTHR, 2) fwd_megakernel(Args args) {
;     ...
;             v4u mq[4], mnx[4]; f32x4 xq[8], xnx[8]; float v[4][8];
;             int m = gw;
;             if (m < MP) { RP_LOAD4(mq, Z + (size_t)m * DM); RP_LOADX(xq, x_prompt + (size_t)m * DM); }
.LBB0_1008:
	s_cmp_lt_i32 s46, 7
	s_cselect_b64 s[4:5], -1, 0
	s_and_b64 s[0:1], s[4:5], s[0:1]
	s_andn2_b64 vcc, exec, s[0:1]
	s_cbranch_vccnz .LBB0_1018
	s_cmpk_gt_i32 s86, 0x7fff
	s_cbranch_scc1 .LBB0_1014
	s_ashr_i32 s87, s86, 31
	s_lshl_b64 s[4:5], s[86:87], 12
	s_add_u32 s8, s12, s4
	s_addc_u32 s9, s13, s5
	v_lshlrev_b32_e32 v0, 4, v164
	global_load_dwordx4 v[92:95], v0, s[8:9]
	global_load_dwordx4 v[88:91], v0, s[8:9] offset:1024
	global_load_dwordx4 v[84:87], v0, s[8:9] offset:2048
	global_load_dwordx4 v[80:83], v0, s[8:9] offset:3072
	s_lshl_b64 s[8:9], s[86:87], 13
	s_add_u32 s8, s36, s8
	s_addc_u32 s9, s37, s9
	v_lshlrev_b32_e32 v96, 5, v164
	v_mov_b32_e32 v97, 0
	v_lshl_add_u64 v[0:1], s[8:9], 0, v[96:97]
	global_load_dwordx4 v[32:35], v96, s[8:9] offset:16
	global_load_dwordx4 v[44:47], v96, s[8:9]
	global_load_dwordx4 v[16:19], v96, s[8:9] offset:2064
	global_load_dwordx4 v[20:23], v96, s[8:9] offset:2048
	s_mov_b64 s[8:9], 0x1000
	v_lshl_add_u64 v[2:3], v[0:1], 0, s[8:9]
	s_movk_i32 s8, 0x1000
	v_add_co_u32_e32 v24, vcc, s8, v0
	s_mov_b64 s[8:9], 0x1800
	s_nop 0
	v_addc_co_u32_e32 v25, vcc, 0, v1, vcc
	global_load_dwordx4 v[12:15], v[24:25], off
	global_load_dwordx4 v[8:11], v[2:3], off offset:16
	v_lshl_add_u64 v[26:27], v[0:1], 0, s[8:9]
	global_load_dwordx4 v[4:7], v[24:25], off offset:2048
	global_load_dwordx4 v[0:3], v[26:27], off offset:16
	v_mbcnt_lo_u32_b32 v24, -1, 0
	v_mbcnt_hi_u32_b32 v24, -1, v24
	v_and_b32_e32 v25, 64, v24
	v_add_u32_e32 v25, 64, v25
	v_xor_b32_e32 v26, 1, v24
	v_cmp_lt_i32_e32 vcc, v26, v25
	s_add_u32 s4, s26, s4
	s_addc_u32 s5, s27, s5
	v_cndmask_b32_e32 v26, v24, v26, vcc
	v_lshlrev_b32_e32 v106, 2, v26
	v_xor_b32_e32 v26, 2, v24
	v_cmp_lt_i32_e32 vcc, v26, v25
	s_add_i32 s16, s86, s34
	s_ashr_i32 s35, s34, 31
	v_cndmask_b32_e32 v26, v24, v26, vcc
	v_lshlrev_b32_e32 v107, 2, v26
	v_xor_b32_e32 v26, 4, v24
	v_cmp_lt_i32_e32 vcc, v26, v25
	s_ashr_i32 s17, s16, 31
	s_lshl_b64 s[8:9], s[34:35], 12
	v_cndmask_b32_e32 v26, v24, v26, vcc
	v_lshlrev_b32_e32 v108, 2, v26
	v_xor_b32_e32 v26, 8, v24
	v_cmp_lt_i32_e32 vcc, v26, v25
	s_lshl_b64 s[10:11], s[16:17], 13
	s_waitcnt lgkmcnt(0)
	v_lshl_add_u64 v[98:99], s[66:67], 0, v[96:97]
	v_cndmask_b32_e32 v26, v24, v26, vcc
	v_lshlrev_b32_e32 v109, 2, v26
	v_xor_b32_e32 v26, 16, v24
	v_cmp_lt_i32_e32 vcc, v26, v25
	s_add_u32 s10, s36, s10
	s_addc_u32 s11, s37, s11
	v_cndmask_b32_e32 v26, v24, v26, vcc
	v_lshlrev_b32_e32 v110, 2, v26
	v_xor_b32_e32 v26, 32, v24
	v_cmp_lt_i32_e32 vcc, v26, v25
	v_mov_b32_e32 v25, v97
	s_lshl_b64 s[16:17], s[16:17], 12
	v_cndmask_b32_e32 v24, v24, v26, vcc
	v_lshlrev_b32_e32 v111, 2, v24
	v_or_b32_e32 v24, 0x1000, v96
	v_lshl_add_u64 v[100:101], s[66:67], 0, v[24:25]
	v_or_b32_e32 v96, 0x1800, v96
	v_and_b32_e32 v24, 63, v162
	v_lshl_add_u64 v[102:103], s[66:67], 0, v[96:97]
	v_lshlrev_b32_e32 v96, 4, v24
	v_lshlrev_b32_e32 v24, 5, v24
	v_lshl_add_u64 v[24:25], s[10:11], 0, v[24:25]
	s_mov_b64 s[10:11], 0x1810
	v_lshl_add_u64 v[104:105], v[24:25], 0, s[10:11]
	s_lshl_b64 s[10:11], s[34:35], 13
	s_add_u32 s16, s44, s16
	s_movk_i32 s18, 0xe7f0
	s_addc_u32 s17, s45, s17
	s_mov_b32 s19, -1
	v_mov_b32_e32 v112, 0x358637bd
	s_mov_b32 s22, 0x800000
	s_mov_b32 s23, s86
	global_load_dwordx4 v[170:173], v[98:99], off offset:16
	global_load_dwordx4 v[174:177], v[98:99], off
	global_load_dwordx4 v[178:181], v[98:99], off offset:2048
	global_load_dwordx4 v[182:185], v[98:99], off offset:2064
	global_load_dwordx4 v[186:189], v[100:101], off
	global_load_dwordx4 v[190:193], v[100:101], off offset:16
	global_load_dwordx4 v[194:197], v[102:103], off
	global_load_dwordx4 v[198:201], v[102:103], off offset:16
	s_waitcnt vmcnt(0)
	s_branch .LBB0_1012
; __global__ void __launch_bounds__(NTHR, 2) fwd_megakernel(Args args) {
;     ...
;                 for (int j = 0; j < 4; ++j) pg8::bf8_to_f32(mq[j], v[j]);
;                 R1_BODY(m);
; #pragma unroll
;                 for (int j = 0; j < 4; ++j) mq[j] = mnx[j];
; #pragma unroll
;                 for (int j = 0; j < 8; ++j) xq[j] = xnx[j];
.LBB0_1011:
	v_lshlrev_b32_e32 v117, 16, v88
	v_and_b32_e32 v124, 0xffff0000, v88
	v_lshlrev_b32_e32 v125, 16, v89
	v_and_b32_e32 v126, 0xffff0000, v89
	v_lshlrev_b32_e32 v127, 16, v90
	v_and_b32_e32 v128, 0xffff0000, v90
	v_lshlrev_b32_e32 v129, 16, v91
	v_and_b32_e32 v130, 0xffff0000, v91
	v_lshlrev_b32_e32 v131, 16, v84
	v_and_b32_e32 v132, 0xffff0000, v84
	v_lshlrev_b32_e32 v133, 16, v85
	v_and_b32_e32 v134, 0xffff0000, v85
	v_lshlrev_b32_e32 v135, 16, v86
	v_and_b32_e32 v136, 0xffff0000, v86
	v_lshlrev_b32_e32 v137, 16, v87
	v_and_b32_e32 v138, 0xffff0000, v87
	v_lshlrev_b32_e32 v113, 16, v92
	v_and_b32_e32 v92, 0xffff0000, v92
	v_mul_f32_e32 v120, v92, v92
	v_lshlrev_b32_e32 v114, 16, v93
	v_fmac_f32_e32 v120, v113, v113
	v_and_b32_e32 v93, 0xffff0000, v93
	v_fmac_f32_e32 v120, v114, v114
	v_lshlrev_b32_e32 v115, 16, v94
	v_fmac_f32_e32 v120, v93, v93
	v_and_b32_e32 v94, 0xffff0000, v94
	v_fmac_f32_e32 v120, v115, v115
	v_lshlrev_b32_e32 v116, 16, v95
	v_fmac_f32_e32 v120, v94, v94
	v_and_b32_e32 v95, 0xffff0000, v95
	v_fmac_f32_e32 v120, v116, v116
	v_fmac_f32_e32 v120, v95, v95
	v_fmac_f32_e32 v120, v117, v117
	v_fmac_f32_e32 v120, v124, v124
	v_fmac_f32_e32 v120, v125, v125
	v_fmac_f32_e32 v120, v126, v126
	v_fmac_f32_e32 v120, v127, v127
	v_fmac_f32_e32 v120, v128, v128
	v_fmac_f32_e32 v120, v129, v129
	v_fmac_f32_e32 v120, v130, v130
	v_fmac_f32_e32 v120, v131, v131
	v_fmac_f32_e32 v120, v132, v132
	v_fmac_f32_e32 v120, v133, v133
	v_fmac_f32_e32 v120, v134, v134
	v_fmac_f32_e32 v120, v135, v135
	v_fmac_f32_e32 v120, v136, v136
	v_fmac_f32_e32 v120, v137, v137
	v_lshlrev_b32_e32 v139, 16, v80
	v_fmac_f32_e32 v120, v138, v138
	v_and_b32_e32 v140, 0xffff0000, v80
	v_fmac_f32_e32 v120, v139, v139
	v_lshlrev_b32_e32 v141, 16, v81
	v_fmac_f32_e32 v120, v140, v140
	v_and_b32_e32 v142, 0xffff0000, v81
	v_fmac_f32_e32 v120, v141, v141
	v_lshlrev_b32_e32 v118, 16, v82
	v_and_b32_e32 v119, 0xffff0000, v82
	v_fmac_f32_e32 v120, v142, v142
	v_pk_mul_f32 v[80:81], v[118:119], v[118:119]
	v_and_b32_e32 v121, 0xffff0000, v83
	v_add_f32_e32 v80, v120, v80
	v_lshlrev_b32_e32 v120, 16, v83
	v_add_f32_e32 v82, v80, v81
	v_pk_mul_f32 v[80:81], v[120:121], v[120:121]
	v_lshl_add_u64 v[122:123], s[4:5], 0, v[96:97]
	v_add_f32_e32 v80, v82, v80
	v_add_f32_e32 v80, v80, v81
	ds_bpermute_b32 v81, v106, v80
	s_add_u32 s4, s4, s8
	s_addc_u32 s5, s5, s9
	s_add_u32 s16, s16, s8
	v_lshl_add_u64 v[104:105], v[104:105], 0, s[10:11]
	s_waitcnt lgkmcnt(0)
	v_add_f32_e32 v80, v80, v81
	ds_bpermute_b32 v81, v107, v80
	s_addc_u32 s17, s17, s9
	s_waitcnt lgkmcnt(0)
	v_add_f32_e32 v80, v80, v81
	ds_bpermute_b32 v81, v108, v80
	s_waitcnt lgkmcnt(0)
	v_add_f32_e32 v80, v80, v81
	ds_bpermute_b32 v81, v109, v80
	s_waitcnt lgkmcnt(0)
	v_add_f32_e32 v80, v80, v81
	ds_bpermute_b32 v81, v110, v80
	s_waitcnt lgkmcnt(0)
	v_add_f32_e32 v80, v80, v81
	ds_bpermute_b32 v81, v111, v80
	s_waitcnt lgkmcnt(0)
	v_add_f32_e32 v80, v80, v81
	v_fmamk_f32 v80, v80, 0x3a000000, v112
	v_mul_f32_e32 v81, 0x4b800000, v80
	v_cmp_gt_f32_e32 vcc, s22, v80
	s_nop 1
	v_cndmask_b32_e32 v80, v80, v81, vcc
	v_rsq_f32_e32 v80, v80
	s_nop 0
	v_mul_f32_e32 v81, 0x45800000, v80
	v_cndmask_b32_e32 v143, v80, v81, vcc
	v_mul_f32_e32 v80, v143, v113
	v_fma_f32 v44, v174, v80, v44
	v_mul_f32_e32 v80, v143, v115
	v_fma_f32 v80, v170, v80, v32
	v_mul_f32_e32 v32, v143, v92
	v_fma_f32 v32, v175, v32, v45
	v_mul_f32_e32 v45, v143, v94
	v_fma_f32 v45, v171, v45, v33
	v_mul_f32_e32 v33, v143, v114
	v_fma_f32 v33, v176, v33, v46
	v_mul_f32_e32 v46, v143, v116
	v_fma_f32 v46, v172, v46, v34
	v_mul_f32_e32 v34, v143, v93
	v_fmac_f32_e32 v47, v177, v34
	v_mul_f32_e32 v34, v143, v95
	v_fmac_f32_e32 v35, v173, v34
	v_cvt_pk_bf16_f32 v32, v44, v32
	v_cvt_pk_bf16_f32 v33, v33, v47
	v_cvt_pk_bf16_f32 v34, v80, v45
	v_cvt_pk_bf16_f32 v35, v46, v35
	s_waitcnt vmcnt(0)
	global_store_dwordx4 v[122:123], v[32:35], off
	v_mul_f32_e32 v80, v143, v117
	v_mul_f32_e32 v81, v143, v127
	v_mul_f32_e32 v82, v143, v124
	v_mul_f32_e32 v83, v143, v128
	v_mul_f32_e32 v84, v143, v125
	v_mul_f32_e32 v87, v143, v130
	v_mul_f32_e32 v85, v143, v129
	v_mul_f32_e32 v86, v143, v126
	v_mul_f32_e32 v113, v143, v139
	v_mul_f32_e32 v118, v143, v118
	v_mul_f32_e32 v124, v143, v140
	v_mul_f32_e32 v119, v143, v119
	v_mul_f32_e32 v125, v143, v141
	v_mul_f32_e32 v120, v143, v120
	v_mul_f32_e32 v126, v143, v142
	v_mul_f32_e32 v121, v143, v121
	v_mov_b64_e32 v[94:95], v[26:27]
	v_mov_b64_e32 v[90:91], v[30:31]
	v_mov_b64_e32 v[92:93], v[24:25]
	v_mov_b64_e32 v[88:89], v[28:29]
	s_andn2_b64 vcc, exec, s[20:21]
	v_fma_f32 v20, v178, v80, v20
	v_fma_f32 v32, v182, v81, v16
	v_fma_f32 v16, v179, v82, v21
	v_fma_f32 v21, v183, v83, v17
	v_fma_f32 v17, v180, v84, v22
	v_fmac_f32_e32 v19, v185, v87
	v_fma_f32 v22, v184, v85, v18
	v_fmac_f32_e32 v23, v181, v86
	v_cvt_pk_bf16_f32 v16, v20, v16
	v_cvt_pk_bf16_f32 v17, v17, v23
	v_cvt_pk_bf16_f32 v18, v32, v21
	v_cvt_pk_bf16_f32 v19, v22, v19
	global_store_dwordx4 v[122:123], v[16:19], off offset:1024
	v_mul_f32_e32 v32, v143, v131
	v_mul_f32_e32 v33, v143, v135
	v_mul_f32_e32 v34, v143, v132
	v_mul_f32_e32 v35, v143, v136
	v_mul_f32_e32 v44, v143, v133
	v_mul_f32_e32 v47, v143, v138
	v_mul_f32_e32 v45, v143, v137
	v_mul_f32_e32 v46, v143, v134
	v_mov_b64_e32 v[86:87], v[38:39]
	v_mov_b64_e32 v[84:85], v[36:37]
	v_fma_f32 v12, v186, v32, v12
	v_fma_f32 v16, v190, v33, v8
	v_fma_f32 v8, v187, v34, v13
	v_fma_f32 v13, v191, v35, v9
	v_fma_f32 v9, v188, v44, v14
	v_fmac_f32_e32 v11, v193, v47
	v_fma_f32 v14, v192, v45, v10
	v_fmac_f32_e32 v15, v189, v46
	v_cvt_pk_bf16_f32 v8, v12, v8
	v_cvt_pk_bf16_f32 v9, v9, v15
	v_cvt_pk_bf16_f32 v10, v16, v13
	v_cvt_pk_bf16_f32 v11, v14, v11
	global_store_dwordx4 v[122:123], v[8:11], off offset:2048
	v_mov_b64_e32 v[32:33], v[48:49]
	v_mov_b64_e32 v[44:45], v[52:53]
	v_mov_b64_e32 v[16:17], v[56:57]
	v_mov_b64_e32 v[20:21], v[60:61]
	v_mov_b64_e32 v[8:9], v[64:65]
	v_mov_b64_e32 v[12:13], v[68:69]
	v_mov_b64_e32 v[34:35], v[50:51]
	v_mov_b64_e32 v[46:47], v[54:55]
	v_mov_b64_e32 v[18:19], v[58:59]
	v_mov_b64_e32 v[22:23], v[62:63]
	v_mov_b64_e32 v[10:11], v[66:67]
	v_mov_b64_e32 v[14:15], v[70:71]
	v_fma_f32 v4, v194, v113, v4
	v_fma_f32 v0, v198, v118, v0
	v_fma_f32 v5, v195, v124, v5
	v_fma_f32 v1, v199, v119, v1
	v_fma_f32 v6, v196, v125, v6
	v_fma_f32 v2, v200, v120, v2
	v_fmac_f32_e32 v7, v197, v126
	v_fmac_f32_e32 v3, v201, v121
	v_cvt_pk_bf16_f32 v80, v4, v5
	v_cvt_pk_bf16_f32 v81, v6, v7
	v_cvt_pk_bf16_f32 v82, v0, v1
	v_cvt_pk_bf16_f32 v83, v2, v3
	v_mov_b64_e32 v[0:1], v[72:73]
	v_mov_b64_e32 v[4:5], v[76:77]
	global_store_dwordx4 v[122:123], v[80:83], off offset:3072
	v_mov_b64_e32 v[2:3], v[74:75]
	v_mov_b64_e32 v[6:7], v[78:79]
	v_mov_b64_e32 v[82:83], v[42:43]
	v_mov_b64_e32 v[80:81], v[40:41]
	s_cbranch_vccz .LBB0_1014

.LBB0_1242:
	s_cmp_lt_i32 s46, 10
	s_cselect_b64 s[4:5], -1, 0
	s_and_b64 s[0:1], s[4:5], s[0:1]
	s_andn2_b64 vcc, exec, s[0:1]
	s_cbranch_vccnz .LBB0_1252
	s_cmpk_gt_i32 s86, 0x7fff
	s_cbranch_scc1 .LBB0_1248
	s_ashr_i32 s87, s86, 31
	s_lshl_b64 s[0:1], s[86:87], 12
	v_readlane_b32 s2, v240, 26
	v_readlane_b32 s3, v240, 27
	s_add_u32 s4, s2, s0
	s_addc_u32 s5, s3, s1
	v_lshlrev_b32_e32 v0, 4, v164
	global_load_dwordx4 v[60:63], v0, s[4:5]
	global_load_dwordx4 v[56:59], v0, s[4:5] offset:1024
	global_load_dwordx4 v[52:55], v0, s[4:5] offset:2048
	global_load_dwordx4 v[44:47], v0, s[4:5] offset:3072
	s_add_u32 s4, s26, s0
	s_addc_u32 s5, s27, s1
	global_load_dwordx4 v[48:51], v0, s[4:5]
	global_load_dwordx4 v[40:43], v0, s[4:5] offset:1024
	global_load_dwordx4 v[36:39], v0, s[4:5] offset:2048
	global_load_dwordx4 v[32:35], v0, s[4:5] offset:3072
	v_mbcnt_lo_u32_b32 v0, -1, 0
	v_mbcnt_hi_u32_b32 v0, -1, v0
	v_and_b32_e32 v1, 64, v0
	v_add_u32_e32 v1, 64, v1
	v_xor_b32_e32 v2, 1, v0
	v_cmp_lt_i32_e32 vcc, v2, v1
	s_add_u32 s0, s44, s0
	s_addc_u32 s1, s45, s1
	v_cndmask_b32_e32 v2, v0, v2, vcc
	v_lshlrev_b32_e32 v80, 2, v2
	v_xor_b32_e32 v2, 2, v0
	v_cmp_lt_i32_e32 vcc, v2, v1
	s_add_i32 s6, s86, s34
	s_ashr_i32 s35, s34, 31
	v_cndmask_b32_e32 v2, v0, v2, vcc
	v_lshlrev_b32_e32 v81, 2, v2
	v_xor_b32_e32 v2, 4, v0
	v_cmp_lt_i32_e32 vcc, v2, v1
	s_ashr_i32 s7, s6, 31
	s_lshl_b64 s[4:5], s[34:35], 12
	v_cndmask_b32_e32 v2, v0, v2, vcc
	v_lshlrev_b32_e32 v82, 2, v2
	v_xor_b32_e32 v2, 8, v0
	v_cmp_lt_i32_e32 vcc, v2, v1
	s_lshl_b64 s[8:9], s[6:7], 12
	v_lshlrev_b32_e32 v64, 5, v164
	v_cndmask_b32_e32 v2, v0, v2, vcc
	v_lshlrev_b32_e32 v83, 2, v2
	v_xor_b32_e32 v2, 16, v0
	v_cmp_lt_i32_e32 vcc, v2, v1
	v_mov_b32_e32 v65, 0
	s_add_u32 s6, s44, s8
	v_cndmask_b32_e32 v2, v0, v2, vcc
	v_lshlrev_b32_e32 v84, 2, v2
	v_xor_b32_e32 v2, 32, v0
	v_cmp_lt_i32_e32 vcc, v2, v1
	v_mov_b32_e32 v1, v65
	s_addc_u32 s7, s45, s9
	v_cndmask_b32_e32 v0, v0, v2, vcc
	v_lshlrev_b32_e32 v85, 2, v0
	v_or_b32_e32 v0, 0x1000, v64
	v_lshl_add_u64 v[66:67], s[14:15], 0, v[64:65]
	v_lshl_add_u64 v[68:69], s[14:15], 0, v[0:1]
	v_or_b32_e32 v64, 0x1800, v64
	v_and_b32_e32 v0, 63, v162
	s_add_u32 s8, s26, s8
	s_mov_b32 s10, 0x358637bd
	v_readlane_b32 s3, v240, 9
	v_lshl_add_u64 v[70:71], s[14:15], 0, v[64:65]
	v_lshlrev_b32_e32 v64, 4, v0
	s_addc_u32 s9, s27, s9
	s_mov_b32 s18, 0x8100000
	s_mov_b32 s11, 0x3a000000
	s_mov_b32 s19, 0x800000
	v_mov_b32_e32 v72, 0x358637bd
	s_mov_b32 s20, s86
	global_load_dwordx4 v[170:173], v[66:67], off offset:16
	global_load_dwordx4 v[174:177], v[66:67], off
	global_load_dwordx4 v[178:181], v[66:67], off offset:2048
	global_load_dwordx4 v[182:185], v[66:67], off offset:2064
	global_load_dwordx4 v[186:189], v[68:69], off
	global_load_dwordx4 v[190:193], v[68:69], off offset:16
	global_load_dwordx4 v[194:197], v[70:71], off
	global_load_dwordx4 v[198:201], v[70:71], off offset:16
	s_waitcnt vmcnt(0)
	s_branch .LBB0_1246
.LBB0_1245:
	v_and_b32_e32 v95, 0xffff0000, v48
	v_lshlrev_b32_e32 v94, 16, v48
	v_lshlrev_b32_e32 v106, 16, v50
	v_and_b32_e32 v107, 0xffff0000, v50
	v_mul_f32_e32 v50, v95, v95
	v_lshlrev_b32_e32 v104, 16, v49
	v_fmac_f32_e32 v50, v94, v94
	v_and_b32_e32 v105, 0xffff0000, v49
	v_fmac_f32_e32 v50, v104, v104
	v_fmac_f32_e32 v50, v105, v105
	v_lshlrev_b32_e32 v86, 16, v60
	v_and_b32_e32 v60, 0xffff0000, v60
	v_fmac_f32_e32 v50, v106, v106
	v_lshlrev_b32_e32 v110, 16, v40
	v_and_b32_e32 v111, 0xffff0000, v40
	v_lshlrev_b32_e32 v112, 16, v41
	v_and_b32_e32 v113, 0xffff0000, v41
	v_lshlrev_b32_e32 v114, 16, v42
	v_and_b32_e32 v115, 0xffff0000, v42
	v_lshlrev_b32_e32 v116, 16, v43
	v_and_b32_e32 v117, 0xffff0000, v43
	v_lshlrev_b32_e32 v118, 16, v36
	v_and_b32_e32 v119, 0xffff0000, v36
	v_lshlrev_b32_e32 v120, 16, v37
	v_and_b32_e32 v121, 0xffff0000, v37
	v_lshlrev_b32_e32 v122, 16, v38
	v_and_b32_e32 v123, 0xffff0000, v38
	v_lshlrev_b32_e32 v124, 16, v39
	v_and_b32_e32 v125, 0xffff0000, v39
	v_mul_f32_e32 v73, v60, v60
	v_lshlrev_b32_e32 v108, 16, v51
	v_fmac_f32_e32 v50, v107, v107
	v_lshlrev_b32_e32 v87, 16, v61
	v_fmac_f32_e32 v73, v86, v86
	v_and_b32_e32 v109, 0xffff0000, v51
	v_fmac_f32_e32 v50, v108, v108
	v_and_b32_e32 v61, 0xffff0000, v61
	v_fmac_f32_e32 v73, v87, v87
	v_fmac_f32_e32 v50, v109, v109
	v_lshlrev_b32_e32 v88, 16, v62
	v_fmac_f32_e32 v73, v61, v61
	v_fmac_f32_e32 v50, v110, v110
	v_and_b32_e32 v62, 0xffff0000, v62
	v_fmac_f32_e32 v73, v88, v88
	v_fmac_f32_e32 v50, v111, v111
	v_lshlrev_b32_e32 v89, 16, v63
	v_fmac_f32_e32 v73, v62, v62
	v_fmac_f32_e32 v50, v112, v112
	v_and_b32_e32 v63, 0xffff0000, v63
	v_fmac_f32_e32 v73, v89, v89
	v_fmac_f32_e32 v50, v113, v113
	v_lshlrev_b32_e32 v90, 16, v56
	v_fmac_f32_e32 v73, v63, v63
	v_fmac_f32_e32 v50, v114, v114
	v_and_b32_e32 v56, 0xffff0000, v56
	v_fmac_f32_e32 v73, v90, v90
	v_fmac_f32_e32 v50, v115, v115
	v_lshlrev_b32_e32 v91, 16, v57
	v_fmac_f32_e32 v73, v56, v56
	v_fmac_f32_e32 v50, v116, v116
	v_and_b32_e32 v57, 0xffff0000, v57
	v_fmac_f32_e32 v73, v91, v91
	v_fmac_f32_e32 v50, v117, v117
	v_lshlrev_b32_e32 v92, 16, v58
	v_fmac_f32_e32 v73, v57, v57
	v_fmac_f32_e32 v50, v118, v118
	v_and_b32_e32 v58, 0xffff0000, v58
	v_fmac_f32_e32 v73, v92, v92
	v_fmac_f32_e32 v50, v119, v119
	v_lshlrev_b32_e32 v93, 16, v59
	v_fmac_f32_e32 v73, v58, v58
	v_fmac_f32_e32 v50, v120, v120
	v_and_b32_e32 v59, 0xffff0000, v59
	v_fmac_f32_e32 v73, v93, v93
	v_fmac_f32_e32 v50, v121, v121
	v_lshlrev_b32_e32 v96, 16, v52
	v_fmac_f32_e32 v73, v59, v59
	v_fmac_f32_e32 v50, v122, v122
	v_and_b32_e32 v97, 0xffff0000, v52
	v_fmac_f32_e32 v73, v96, v96
	v_fmac_f32_e32 v50, v123, v123
	v_lshlrev_b32_e32 v98, 16, v53
	v_fmac_f32_e32 v73, v97, v97
	v_fmac_f32_e32 v50, v124, v124
	v_and_b32_e32 v99, 0xffff0000, v53
	v_fmac_f32_e32 v73, v98, v98
	v_fmac_f32_e32 v50, v125, v125
	v_lshlrev_b32_e32 v126, 16, v32
	v_lshlrev_b32_e32 v100, 16, v54
	v_fmac_f32_e32 v73, v99, v99
	v_and_b32_e32 v127, 0xffff0000, v32
	v_fmac_f32_e32 v50, v126, v126
	v_and_b32_e32 v54, 0xffff0000, v54
	v_fmac_f32_e32 v73, v100, v100
	v_lshlrev_b32_e32 v128, 16, v33
	v_fmac_f32_e32 v50, v127, v127
	v_lshlrev_b32_e32 v101, 16, v55
	v_fmac_f32_e32 v73, v54, v54
	v_and_b32_e32 v129, 0xffff0000, v33
	v_fmac_f32_e32 v50, v128, v128
	v_lshlrev_b32_e32 v48, 16, v34
	v_and_b32_e32 v49, 0xffff0000, v34
	v_and_b32_e32 v55, 0xffff0000, v55
	v_fmac_f32_e32 v73, v101, v101
	v_fmac_f32_e32 v50, v129, v129
	v_pk_mul_f32 v[32:33], v[48:49], v[48:49]
	v_lshlrev_b32_e32 v102, 16, v44
	v_fmac_f32_e32 v73, v55, v55
	v_add_f32_e32 v32, v50, v32
	v_lshlrev_b32_e32 v50, 16, v35
	v_and_b32_e32 v51, 0xffff0000, v35
	v_and_b32_e32 v103, 0xffff0000, v44
	v_lshlrev_b32_e32 v74, 16, v45
	v_and_b32_e32 v75, 0xffff0000, v45
	v_add_f32_e32 v34, v32, v33
	v_pk_mul_f32 v[32:33], v[50:51], v[50:51]
	v_fmac_f32_e32 v73, v102, v102
	v_pk_mul_f32 v[44:45], v[74:75], v[74:75]
	v_add_f32_e32 v32, v34, v32
	v_fmac_f32_e32 v73, v103, v103
	v_lshlrev_b32_e32 v76, 16, v46
	v_and_b32_e32 v77, 0xffff0000, v46
	v_add_f32_e32 v32, v32, v33
	v_add_f32_e32 v33, v73, v44
	v_pk_mul_f32 v[52:53], v[76:77], v[76:77]
	v_add_f32_e32 v33, v33, v45
	v_lshlrev_b32_e32 v78, 16, v47
	v_and_b32_e32 v79, 0xffff0000, v47
	v_add_f32_e32 v33, v33, v52
	v_pk_mul_f32 v[46:47], v[78:79], v[78:79]
	v_add_f32_e32 v33, v33, v53
	v_add_f32_e32 v33, v33, v46
	ds_bpermute_b32 v34, v80, v32
	v_add_f32_e32 v33, v33, v47
	ds_bpermute_b32 v35, v80, v33
	s_waitcnt lgkmcnt(0)
	v_add_f32_e32 v32, v32, v34
	ds_bpermute_b32 v34, v81, v32
	v_add_f32_e32 v33, v33, v35
	ds_bpermute_b32 v35, v81, v33
	s_waitcnt lgkmcnt(1)
	v_add_f32_e32 v32, v32, v34
	ds_bpermute_b32 v34, v82, v32
	s_waitcnt lgkmcnt(1)
	v_add_f32_e32 v33, v33, v35
	ds_bpermute_b32 v35, v82, v33
	s_waitcnt lgkmcnt(1)
	v_add_f32_e32 v32, v32, v34
	ds_bpermute_b32 v34, v83, v32
	s_waitcnt lgkmcnt(1)
	v_add_f32_e32 v33, v33, v35
	ds_bpermute_b32 v35, v83, v33
	s_waitcnt lgkmcnt(1)
	v_add_f32_e32 v32, v32, v34
	ds_bpermute_b32 v34, v84, v32
	s_waitcnt lgkmcnt(1)
	v_add_f32_e32 v33, v33, v35
	ds_bpermute_b32 v35, v84, v33
	s_waitcnt lgkmcnt(1)
	v_add_f32_e32 v32, v32, v34
	ds_bpermute_b32 v34, v85, v32
	s_waitcnt lgkmcnt(1)
	v_add_f32_e32 v33, v33, v35
	ds_bpermute_b32 v73, v85, v33
	s_waitcnt lgkmcnt(1)
	v_add_f32_e32 v32, v32, v34
	v_mul_f32_e32 v32, 0x3a000000, v32
	s_waitcnt lgkmcnt(0)
	v_pk_add_f32 v[32:33], v[32:33], v[72:73]
	s_nop 0
	v_pk_mul_f32 v[34:35], v[32:33], s[10:11]
	s_nop 0
	v_fmac_f32_e32 v35, v32, v34
	v_mul_f32_e32 v32, 0x4b800000, v35
	v_cmp_gt_f32_e32 vcc, s19, v35
	s_nop 1
	v_cndmask_b32_e32 v32, v35, v32, vcc
	v_rsq_f32_e32 v32, v32
	s_nop 0
	v_mul_f32_e32 v33, 0x45800000, v32
	v_cndmask_b32_e32 v73, v32, v33, vcc
	v_mul_f32_e32 v32, v73, v86
	v_fmac_f32_e32 v94, v174, v32
	v_mul_f32_e32 v32, v73, v88
	v_fmac_f32_e32 v106, v170, v32
	v_mul_f32_e32 v32, v73, v60
	v_fmac_f32_e32 v95, v175, v32
	v_mul_f32_e32 v32, v73, v62
	v_fmac_f32_e32 v107, v171, v32
	v_mul_f32_e32 v32, v73, v87
	v_fmac_f32_e32 v104, v176, v32
	v_mul_f32_e32 v32, v73, v89
	v_fmac_f32_e32 v108, v172, v32
	v_mul_f32_e32 v32, v73, v61
	v_fmac_f32_e32 v105, v177, v32
	v_mul_f32_e32 v32, v73, v63
	v_lshl_add_u64 v[36:37], s[0:1], 0, v[64:65]
	v_fmac_f32_e32 v109, v173, v32
	v_cvt_pk_bf16_f32 v32, v94, v95
	v_add_co_u32_e32 v94, vcc, s18, v36
	v_cvt_pk_bf16_f32 v33, v104, v105
	v_cvt_pk_bf16_f32 v34, v106, v107
	v_cvt_pk_bf16_f32 v35, v108, v109
	v_mul_f32_e32 v40, v73, v90
	s_nop 0
	v_addc_co_u32_e32 v95, vcc, 0, v37, vcc
	s_waitcnt vmcnt(0)
	global_store_dwordx4 v[94:95], v[32:35], off
	v_mul_f32_e32 v41, v73, v100
	v_mul_f32_e32 v42, v73, v97
	v_mul_f32_e32 v43, v73, v54
	v_mul_f32_e32 v44, v73, v98
	v_mul_f32_e32 v45, v73, v101
	v_mul_f32_e32 v46, v73, v99
	v_mul_f32_e32 v47, v73, v55
	s_add_u32 s0, s0, s4
	s_addc_u32 s1, s1, s5
	s_add_u32 s6, s6, s4
	v_mul_f32_e32 v76, v73, v76
	v_mul_f32_e32 v97, v73, v103
	v_mul_f32_e32 v77, v73, v77
	v_mul_f32_e32 v74, v73, v74
	v_mul_f32_e32 v78, v73, v78
	v_mul_f32_e32 v75, v73, v75
	s_addc_u32 s7, s7, s5
	v_mov_b64_e32 v[54:55], v[6:7]
	v_mov_b64_e32 v[62:63], v[14:15]
	s_add_u32 s8, s8, s4
	v_mov_b64_e32 v[52:53], v[4:5]
	v_mov_b64_e32 v[60:61], v[12:13]
	s_addc_u32 s9, s9, s5
	s_andn2_b64 vcc, exec, s[16:17]
	v_fmac_f32_e32 v110, v178, v40
	v_mul_f32_e32 v32, v73, v92
	v_fmac_f32_e32 v114, v182, v32
	v_mul_f32_e32 v32, v73, v56
	v_fmac_f32_e32 v111, v179, v32
	v_mul_f32_e32 v32, v73, v58
	v_fmac_f32_e32 v115, v183, v32
	v_mul_f32_e32 v32, v73, v91
	v_fmac_f32_e32 v112, v180, v32
	v_mul_f32_e32 v32, v73, v93
	v_fmac_f32_e32 v116, v184, v32
	v_mul_f32_e32 v32, v73, v57
	v_fmac_f32_e32 v113, v181, v32
	v_mul_f32_e32 v32, v73, v59
	v_fmac_f32_e32 v117, v185, v32
	v_cvt_pk_bf16_f32 v32, v110, v111
	v_cvt_pk_bf16_f32 v33, v112, v113
	v_cvt_pk_bf16_f32 v34, v114, v115
	v_cvt_pk_bf16_f32 v35, v116, v117
	global_store_dwordx4 v[94:95], v[32:35], off offset:1024
	v_mul_f32_e32 v40, v73, v96
	v_mul_f32_e32 v96, v73, v102
	v_mul_f32_e32 v73, v73, v79
	v_mov_b64_e32 v[58:59], v[10:11]
	v_mov_b64_e32 v[56:57], v[8:9]
	v_fmac_f32_e32 v118, v186, v40
	v_fmac_f32_e32 v122, v190, v41
	v_fmac_f32_e32 v119, v187, v42
	v_fmac_f32_e32 v123, v191, v43
	v_fmac_f32_e32 v120, v188, v44
	v_fmac_f32_e32 v124, v192, v45
	v_fmac_f32_e32 v121, v189, v46
	v_fmac_f32_e32 v125, v193, v47
	v_cvt_pk_bf16_f32 v32, v118, v119
	v_cvt_pk_bf16_f32 v33, v120, v121
	v_cvt_pk_bf16_f32 v34, v122, v123
	v_cvt_pk_bf16_f32 v35, v124, v125
	global_store_dwordx4 v[94:95], v[32:35], off offset:2048
	s_nop 1
	v_mov_b64_e32 v[46:47], v[2:3]
	v_mov_b64_e32 v[34:35], v[18:19]
	v_mov_b64_e32 v[38:39], v[22:23]
	v_mov_b64_e32 v[42:43], v[26:27]
	v_mov_b64_e32 v[44:45], v[0:1]
	v_mov_b64_e32 v[32:33], v[16:17]
	v_mov_b64_e32 v[36:37], v[20:21]
	v_mov_b64_e32 v[40:41], v[24:25]
	v_fmac_f32_e32 v126, v194, v96
	v_fmac_f32_e32 v48, v198, v76
	v_fmac_f32_e32 v49, v199, v77
	v_fmac_f32_e32 v50, v200, v78
	v_fmac_f32_e32 v51, v201, v73
	v_fmac_f32_e32 v127, v195, v97
	v_fmac_f32_e32 v128, v196, v74
	v_fmac_f32_e32 v129, v197, v75
	v_cvt_pk_bf16_f32 v74, v126, v127
	v_cvt_pk_bf16_f32 v75, v128, v129
	v_cvt_pk_bf16_f32 v76, v48, v49
	v_cvt_pk_bf16_f32 v77, v50, v51
	v_mov_b64_e32 v[50:51], v[30:31]
	v_mov_b64_e32 v[48:49], v[28:29]
	global_store_dwordx4 v[94:95], v[74:77], off offset:3072
	s_cbranch_vccz .LBB0_1248

.LBB0_1394:
	s_cmp_lt_i32 s46, 13
	s_cselect_b64 s[0:1], -1, 0
	s_and_b64 s[0:1], s[0:1], s[28:29]
	s_cmp_lt_i32 s86, 0x8400
	s_cselect_b64 s[4:5], -1, 0
	s_and_b64 s[0:1], s[0:1], s[4:5]
	s_andn2_b64 vcc, exec, s[0:1]
	s_cbranch_vccnz .LBB0_1399
	s_ashr_i32 s87, s86, 31
	s_lshl_b64 s[0:1], s[86:87], 12
	s_add_u32 s4, s12, s0
	s_addc_u32 s5, s13, s1
	v_readlane_b32 s2, v240, 26
	v_readlane_b32 s3, v240, 27
	s_add_u32 s0, s2, s0
	v_lshlrev_b32_e32 v8, 4, v164
	s_addc_u32 s1, s3, s1
	global_load_dwordx4 v[60:63], v8, s[4:5]
	global_load_dwordx4 v[56:59], v8, s[4:5] offset:1024
	global_load_dwordx4 v[52:55], v8, s[4:5] offset:2048
	global_load_dwordx4 v[48:51], v8, s[4:5] offset:3072
	global_load_dwordx4 v[44:47], v8, s[0:1]
	global_load_dwordx4 v[40:43], v8, s[0:1] offset:1024
	global_load_dwordx4 v[4:7], v8, s[0:1] offset:2048
	global_load_dwordx4 v[0:3], v8, s[0:1] offset:3072
	v_mbcnt_lo_u32_b32 v8, -1, 0
	v_mbcnt_hi_u32_b32 v8, -1, v8
	v_and_b32_e32 v9, 64, v8
	v_add_u32_e32 v9, 64, v9
	v_xor_b32_e32 v10, 1, v8
	v_cmp_lt_i32_e32 vcc, v10, v9
	s_lshl_b64 s[0:1], s[86:87], 13
	v_and_b32_e32 v12, 63, v162
	v_cndmask_b32_e32 v10, v8, v10, vcc
	v_lshlrev_b32_e32 v74, 2, v10
	v_xor_b32_e32 v10, 2, v8
	v_cmp_lt_i32_e32 vcc, v10, v9
	s_add_u32 s0, s26, s0
	s_addc_u32 s1, s27, s1
	v_cndmask_b32_e32 v10, v8, v10, vcc
	v_lshlrev_b32_e32 v75, 2, v10
	v_xor_b32_e32 v10, 4, v8
	v_cmp_lt_i32_e32 vcc, v10, v9
	s_add_i32 s2, s86, s34
	s_ashr_i32 s35, s34, 31
	v_cndmask_b32_e32 v10, v8, v10, vcc
	v_lshlrev_b32_e32 v76, 2, v10
	v_xor_b32_e32 v10, 8, v8
	v_cmp_lt_i32_e32 vcc, v10, v9
	s_ashr_i32 s3, s2, 31
	s_lshl_b64 s[2:3], s[2:3], 12
	v_cndmask_b32_e32 v10, v8, v10, vcc
	v_lshlrev_b32_e32 v77, 2, v10
	v_xor_b32_e32 v10, 16, v8
	v_cmp_lt_i32_e32 vcc, v10, v9
	v_mov_b32_e32 v80, 0x358637bd
	s_mov_b32 s6, 0x800000
	v_cndmask_b32_e32 v10, v8, v10, vcc
	v_lshlrev_b32_e32 v78, 2, v10
	v_xor_b32_e32 v10, 32, v8
	v_cmp_lt_i32_e32 vcc, v10, v9
	v_mov_b32_e32 v9, 0
	v_mov_b32_e32 v11, v9
	v_cndmask_b32_e32 v8, v8, v10, vcc
	v_lshlrev_b32_e32 v79, 2, v8
	v_lshlrev_b32_e32 v8, 5, v164
	v_lshl_add_u64 v[64:65], s[24:25], 0, v[8:9]
	v_or_b32_e32 v10, 0x1000, v8
	v_or_b32_e32 v8, 0x1800, v8
	v_lshl_add_u64 v[68:69], s[24:25], 0, v[8:9]
	v_lshlrev_b32_e32 v8, 5, v12
	v_lshl_add_u64 v[66:67], s[24:25], 0, v[10:11]
	v_lshl_add_u64 v[10:11], s[0:1], 0, v[8:9]
	s_mov_b64 s[0:1], 0x1810
	v_lshl_add_u64 v[70:71], v[10:11], 0, s[0:1]
	s_lshl_b64 s[0:1], s[34:35], 13
	s_add_u32 s2, s44, s2
	v_lshlrev_b32_e32 v8, 4, v12
	s_addc_u32 s3, s45, s3
	v_lshl_add_u64 v[8:9], s[2:3], 0, v[8:9]
	s_mov_b64 s[2:3], 0x15800c00
	v_lshl_add_u64 v[72:73], v[8:9], 0, s[2:3]
	s_lshl_b64 s[2:3], s[34:35], 12
	s_movk_i32 s7, 0xf000
	global_load_dwordx4 v[170:173], v[64:65], off
	global_load_dwordx4 v[174:177], v[64:65], off offset:16
	global_load_dwordx4 v[178:181], v[64:65], off offset:2048
	global_load_dwordx4 v[182:185], v[64:65], off offset:2064
	global_load_dwordx4 v[186:189], v[66:67], off
	global_load_dwordx4 v[190:193], v[66:67], off offset:16
	global_load_dwordx4 v[194:197], v[68:69], off
	global_load_dwordx4 v[198:201], v[68:69], off offset:16
	s_waitcnt vmcnt(0)
	s_branch .LBB0_1397
.LBB0_1396:
	v_lshlrev_b32_e32 v96, 16, v60
	v_and_b32_e32 v97, 0xffff0000, v60
	v_pk_mul_f32 v[98:99], v[96:97], v[96:97]
	v_lshlrev_b32_e32 v60, 16, v61
	v_and_b32_e32 v61, 0xffff0000, v61
	v_pk_mul_f32 v[100:101], v[60:61], v[60:61]
	v_add_f32_e32 v81, v98, v99
	v_lshlrev_b32_e32 v90, 16, v62
	v_and_b32_e32 v91, 0xffff0000, v62
	v_add_f32_e32 v81, v81, v100
	v_pk_mul_f32 v[92:93], v[90:91], v[90:91]
	v_add_f32_e32 v81, v81, v101
	v_lshlrev_b32_e32 v62, 16, v63
	v_and_b32_e32 v63, 0xffff0000, v63
	v_add_f32_e32 v81, v81, v92
	v_pk_mul_f32 v[94:95], v[62:63], v[62:63]
	v_add_f32_e32 v81, v81, v93
	v_lshlrev_b32_e32 v108, 16, v56
	v_and_b32_e32 v109, 0xffff0000, v56
	v_add_f32_e32 v81, v81, v94
	v_pk_mul_f32 v[110:111], v[108:109], v[108:109]
	v_add_f32_e32 v81, v81, v95
	v_lshlrev_b32_e32 v56, 16, v57
	v_and_b32_e32 v57, 0xffff0000, v57
	v_add_f32_e32 v81, v81, v110
	v_pk_mul_f32 v[112:113], v[56:57], v[56:57]
	v_add_f32_e32 v81, v81, v111
	v_lshlrev_b32_e32 v102, 16, v58
	v_and_b32_e32 v103, 0xffff0000, v58
	v_add_f32_e32 v81, v81, v112
	v_pk_mul_f32 v[104:105], v[102:103], v[102:103]
	v_add_f32_e32 v81, v81, v113
	v_lshlrev_b32_e32 v58, 16, v59
	v_and_b32_e32 v59, 0xffff0000, v59
	v_add_f32_e32 v81, v81, v104
	v_pk_mul_f32 v[106:107], v[58:59], v[58:59]
	v_add_f32_e32 v81, v81, v105
	v_lshlrev_b32_e32 v120, 16, v52
	v_and_b32_e32 v121, 0xffff0000, v52
	v_add_f32_e32 v81, v81, v106
	v_pk_mul_f32 v[122:123], v[120:121], v[120:121]
	v_add_f32_e32 v81, v81, v107
	v_lshlrev_b32_e32 v52, 16, v53
	v_and_b32_e32 v53, 0xffff0000, v53
	v_add_f32_e32 v81, v81, v122
	v_pk_mul_f32 v[124:125], v[52:53], v[52:53]
	v_add_f32_e32 v81, v81, v123
	v_lshlrev_b32_e32 v114, 16, v54
	v_and_b32_e32 v115, 0xffff0000, v54
	v_add_f32_e32 v81, v81, v124
	v_pk_mul_f32 v[116:117], v[114:115], v[114:115]
	v_add_f32_e32 v81, v81, v125
	v_lshlrev_b32_e32 v54, 16, v55
	v_and_b32_e32 v55, 0xffff0000, v55
	v_add_f32_e32 v81, v81, v116
	v_pk_mul_f32 v[118:119], v[54:55], v[54:55]
	v_add_f32_e32 v81, v81, v117
	v_lshlrev_b32_e32 v132, 16, v48
	v_and_b32_e32 v133, 0xffff0000, v48
	v_add_f32_e32 v81, v81, v118
	v_pk_mul_f32 v[134:135], v[132:133], v[132:133]
	v_add_f32_e32 v81, v81, v119
	v_lshlrev_b32_e32 v136, 16, v49
	v_and_b32_e32 v137, 0xffff0000, v49
	v_add_f32_e32 v81, v81, v134
	v_pk_mul_f32 v[48:49], v[136:137], v[136:137]
	v_add_f32_e32 v81, v81, v135
	v_lshlrev_b32_e32 v126, 16, v50
	v_and_b32_e32 v127, 0xffff0000, v50
	v_add_f32_e32 v48, v81, v48
	v_pk_mul_f32 v[128:129], v[126:127], v[126:127]
	v_add_f32_e32 v48, v48, v49
	v_lshlrev_b32_e32 v130, 16, v51
	v_and_b32_e32 v131, 0xffff0000, v51
	v_add_f32_e32 v48, v48, v128
	v_pk_mul_f32 v[50:51], v[130:131], v[130:131]
	v_add_f32_e32 v48, v48, v129
	v_add_f32_e32 v48, v48, v50
	v_add_f32_e32 v48, v48, v51
	ds_bpermute_b32 v49, v74, v48
	v_and_b32_e32 v51, 0xffff0000, v47
	v_and_b32_e32 v93, 0xffff0000, v45
	v_lshl_add_u64 v[72:73], v[72:73], 0, s[2:3]
	s_waitcnt lgkmcnt(0)
	v_add_f32_e32 v48, v48, v49
	ds_bpermute_b32 v49, v75, v48
	s_waitcnt lgkmcnt(0)
	v_add_f32_e32 v48, v48, v49
	ds_bpermute_b32 v49, v76, v48
	s_waitcnt lgkmcnt(0)
	v_add_f32_e32 v48, v48, v49
	ds_bpermute_b32 v49, v77, v48
	s_waitcnt lgkmcnt(0)
	v_add_f32_e32 v49, v48, v49
	ds_bpermute_b32 v50, v78, v49
	v_lshlrev_b32_e32 v48, 16, v46
	s_waitcnt lgkmcnt(0)
	v_add_f32_e32 v81, v49, v50
	ds_bpermute_b32 v92, v79, v81
	v_lshlrev_b32_e32 v50, 16, v47
	v_and_b32_e32 v49, 0xffff0000, v46
	v_lshlrev_b32_e32 v46, 16, v44
	s_waitcnt lgkmcnt(0)
	v_add_f32_e32 v47, v81, v92
	v_fmamk_f32 v47, v47, 0x3a000000, v80
	v_mul_f32_e32 v81, 0x4b800000, v47
	v_cmp_gt_f32_e32 vcc, s6, v47
	v_lshlrev_b32_e32 v92, 16, v45
	s_nop 0
	v_cndmask_b32_e32 v47, v47, v81, vcc
	v_rsq_f32_e32 v81, v47
	v_and_b32_e32 v47, 0xffff0000, v44
	v_mul_f32_e32 v44, 0x45800000, v81
	v_cndmask_b32_e32 v94, v81, v44, vcc
	v_pk_mul_f32 v[44:45], v[94:95], v[96:97] op_sel_hi:[0,1]
	v_pk_fma_f32 v[44:45], v[170:171], v[44:45], v[46:47]
	v_pk_mul_f32 v[46:47], v[94:95], v[90:91] op_sel_hi:[0,1]
	v_pk_fma_f32 v[48:49], v[174:175], v[46:47], v[48:49]
	v_pk_mul_f32 v[46:47], v[94:95], v[60:61] op_sel_hi:[0,1]
	v_pk_mul_f32 v[60:61], v[94:95], v[62:63] op_sel_hi:[0,1]
	v_pk_fma_f32 v[50:51], v[176:177], v[60:61], v[50:51]
	v_add_co_u32_e32 v60, vcc, s7, v70
	v_pk_fma_f32 v[46:47], v[172:173], v[46:47], v[92:93]
	s_nop 0
	v_addc_co_u32_e32 v61, vcc, -1, v71, vcc
	s_waitcnt vmcnt(0)
	global_store_dwordx4 v[60:61], v[44:47], off offset:-2064
	global_store_dwordx4 v[60:61], v[48:51], off offset:-2048
	v_lshlrev_b32_e32 v62, 16, v42
	v_and_b32_e32 v63, 0xffff0000, v42
	v_lshlrev_b32_e32 v82, 16, v43
	v_and_b32_e32 v83, 0xffff0000, v43
	v_lshlrev_b32_e32 v42, 16, v40
	v_and_b32_e32 v43, 0xffff0000, v40
	v_lshlrev_b32_e32 v84, 16, v41
	v_and_b32_e32 v85, 0xffff0000, v41
	v_pk_mul_f32 v[40:41], v[94:95], v[108:109] op_sel_hi:[0,1]
	v_pk_mul_f32 v[56:57], v[94:95], v[56:57] op_sel_hi:[0,1]
	v_pk_mul_f32 v[86:87], v[94:95], v[102:103] op_sel_hi:[0,1]
	v_pk_mul_f32 v[58:59], v[94:95], v[58:59] op_sel_hi:[0,1]
	v_pk_mul_f32 v[52:53], v[94:95], v[52:53] op_sel_hi:[0,1]
	v_pk_mul_f32 v[54:55], v[94:95], v[54:55] op_sel_hi:[0,1]
	v_lshlrev_b32_e32 v90, 16, v0
	v_and_b32_e32 v91, 0xffff0000, v0
	v_lshlrev_b32_e32 v92, 16, v1
	v_and_b32_e32 v93, 0xffff0000, v1
	v_pk_mul_f32 v[96:97], v[94:95], v[132:133] op_sel_hi:[0,1]
	v_pk_mul_f32 v[100:101], v[94:95], v[136:137] op_sel_hi:[0,1]
	v_lshlrev_b32_e32 v88, 16, v3
	v_and_b32_e32 v89, 0xffff0000, v3
	v_pk_mul_f32 v[98:99], v[94:95], v[126:127] op_sel_hi:[0,1]
	s_andn2_b64 vcc, exec, s[4:5]
	v_pk_fma_f32 v[40:41], v[178:179], v[40:41], v[42:43]
	v_pk_fma_f32 v[42:43], v[180:181], v[56:57], v[84:85]
	v_pk_fma_f32 v[44:45], v[182:183], v[86:87], v[62:63]
	v_pk_fma_f32 v[46:47], v[184:185], v[58:59], v[82:83]
	global_store_dwordx4 v[60:61], v[40:43], off offset:-16
	global_store_dwordx4 v[70:71], v[44:47], off offset:-4096
	v_lshlrev_b32_e32 v48, 16, v6
	v_and_b32_e32 v49, 0xffff0000, v6
	v_lshlrev_b32_e32 v50, 16, v7
	v_and_b32_e32 v51, 0xffff0000, v7
	v_lshlrev_b32_e32 v6, 16, v4
	v_and_b32_e32 v7, 0xffff0000, v4
	v_lshlrev_b32_e32 v56, 16, v5
	v_and_b32_e32 v57, 0xffff0000, v5
	v_pk_mul_f32 v[4:5], v[94:95], v[120:121] op_sel_hi:[0,1]
	v_pk_mul_f32 v[58:59], v[94:95], v[114:115] op_sel_hi:[0,1]
	v_lshlrev_b32_e32 v86, 16, v2
	v_and_b32_e32 v87, 0xffff0000, v2
	v_pk_mul_f32 v[94:95], v[94:95], v[130:131] op_sel_hi:[0,1]
	v_mov_b64_e32 v[62:63], v[22:23]
	v_mov_b64_e32 v[0:1], v[24:25]
	v_mov_b64_e32 v[60:61], v[20:21]
	v_mov_b64_e32 v[2:3], v[26:27]
	v_pk_fma_f32 v[4:5], v[186:187], v[4:5], v[6:7]
	v_pk_fma_f32 v[6:7], v[188:189], v[52:53], v[56:57]
	v_pk_fma_f32 v[40:41], v[190:191], v[58:59], v[48:49]
	v_pk_fma_f32 v[42:43], v[192:193], v[54:55], v[50:51]
	global_store_dwordx4 v[70:71], v[4:7], off offset:-2064
	global_store_dwordx4 v[70:71], v[40:43], off offset:-2048
	v_mov_b64_e32 v[50:51], v[10:11]
	v_mov_b64_e32 v[54:55], v[14:15]
	v_mov_b64_e32 v[58:59], v[18:19]
	v_mov_b64_e32 v[4:5], v[28:29]
	v_mov_b64_e32 v[42:43], v[34:35]
	v_mov_b64_e32 v[48:49], v[8:9]
	v_mov_b64_e32 v[52:53], v[12:13]
	v_mov_b64_e32 v[56:57], v[16:17]
	v_mov_b64_e32 v[6:7], v[30:31]
	v_mov_b64_e32 v[40:41], v[32:33]
	v_pk_fma_f32 v[44:45], v[194:195], v[96:97], v[90:91]
	v_pk_fma_f32 v[46:47], v[196:197], v[100:101], v[92:93]
	v_pk_fma_f32 v[82:83], v[198:199], v[98:99], v[86:87]
	v_pk_fma_f32 v[84:85], v[200:201], v[94:95], v[88:89]
	global_store_dwordx4 v[70:71], v[44:47], off offset:-16
	global_store_dwordx4 v[70:71], v[82:85], off
	v_lshl_add_u64 v[70:71], v[70:71], 0, s[0:1]
	v_mov_b64_e32 v[46:47], v[38:39]
	v_mov_b64_e32 v[44:45], v[36:37]
	s_cbranch_vccz .LBB0_1399
